# attention fast loop: balanced fillers (tile DMAs in PV k-step-0 gaps, deferred exps spread over QK gaps), f32 VALU row sums in 4 chains, cross-half max only on the rescale path, SGPR-base LDS-DMA addr
# speedup vs baseline: 1.3552x; 1.0125x over previous
; __device__ __forceinline__ unsigned pk2(float lo, float hi) { f32x2_t v = {lo, hi}; bf16x2_t b = __builtin_convertvector(v, bf16x2_t); return __builtin_bit_cast(unsigned, b); }
; __device__ __forceinline__ void att_qs(bf16x8 (&pn)[4], f32x16 (&o)[4], f32x16& osum, f32x16& negm, const bf16x8 (&qf)[4], float& m_hat, ...
;     ...
;     kf[0] = ATT_KREAD(0); kf[1] = ATT_KREAD(1); kf[2] = ATT_KREAD(2); kf[3] = ATT_KREAD(3);
;     __builtin_amdgcn_sched_barrier(0);
; #pragma unroll
;     for (int i = 0; i < 8; ++i) {
;         if (i == 0) c0 = __builtin_amdgcn_mfma_f32_32x32x16_bf16(kf[0], qf[0], negm, 0, 0, 0);
;         else if (i == 1) c1 = __builtin_amdgcn_mfma_f32_32x32x16_bf16(kf[1], qf[0], negm, 0, 0, 0);
;         else if ((i & 1) == 0) c0 = __builtin_amdgcn_mfma_f32_32x32x16_bf16(kf[i & 3], qf[i >> 1], c0, 0, 0, 0);
;         else c1 = __builtin_amdgcn_mfma_f32_32x32x16_bf16(kf[i & 3], qf[i >> 1], c1, 0, 0, 0);
;         if (i + 4 < 8) kf[i & 3] = ATT_KREAD(i + 4);
;         __builtin_amdgcn_sched_barrier(0);
;     }
;     ...
;     unsigned paw[16];
; #pragma unroll
;     for (int g = 0; g < 8; ++g) { const int b = (4 * g) & 15;
;         const float v0 = __builtin_amdgcn_exp2f(g < 4 ? c0[b] : c1[b]), v1 = __builtin_amdgcn_exp2f(g < 4 ? c0[b + 1] : c1[b + 1]);
;         const float v2 = __builtin_amdgcn_exp2f(g < 4 ? c0[b + 2] : c1[b + 2]), v3 = __builtin_amdgcn_exp2f(g < 4 ? c0[b + 3] : c1[b + 3]);
;         paw[2 * g] = pk2(v0, v1); paw[2 * g + 1] = pk2(v2, v3); }
; #pragma unroll
;     for (int k = 0; k < 4; ++k) { u32x4 w; w.x = paw[4 * k]; w.y = paw[4 * k + 1]; w.z = paw[4 * k + 2]; w.w = paw[4 * k + 3]; pn[k] = __builtin_bit_cast(bf16x8, w); }
.Latt_fast_entry:
	v_mov_b32_e32 v242, s8
	v_mov_b32_e32 v243, s8
	v_mov_b32_e32 v244, s8
	v_mov_b32_e32 v245, s8
	v_mov_b32_e32 v248, v17
	v_mov_b32_e32 v118, v16
	v_readfirstlane_b32 s98, v178
	v_readfirstlane_b32 s99, v179
	v_readfirstlane_b32 s100, v180
	v_readfirstlane_b32 s101, v181
	v_mfma_f32_32x32x16_bf16 v[18:33], v[134:137], v[242:245], v[18:33]
	v_mfma_f32_32x32x16_bf16 v[18:33], v[114:117], v[242:245], v[18:33]
	v_mfma_f32_32x32x16_bf16 v[18:33], v[124:127], v[242:245], v[18:33]
	v_mfma_f32_32x32x16_bf16 v[18:33], v[120:123], v[242:245], v[18:33]
	v_mov_b32_e32 v243, 0
	v_mov_b32_e32 v244, 0
	v_mov_b32_e32 v242, 0
	v_mov_b32_e32 v245, 0
	s_add_i32 s10, s57, 0xffff4000
	s_and_b32 s10, s10, 0xc000
	v_add_u32_e32 v133, s10, v185
	s_add_i32 s9, s57, 0xffff8000
	s_and_b32 s9, s9, 0xc000
	v_add_u32_e32 v132, s9, v177
	ds_read_b128 v[128:131], v132
	ds_read_b128 v[138:141], v132 offset:2048
	ds_read_b128 v[142:145], v132 offset:4096
	ds_read_b128 v[250:253], v132 offset:6144
	s_add_i32 s9, s56, 2
	s_min_u32 s9, s9, s52
	s_lshl_b32 s10, s9, 14
	s_mov_b32 s11, 0
	s_add_u32 s10, s98, s10
	s_addc_u32 s11, s99, 0
	s_and_b32 s9, s57, 0xc000
	s_add_i32 s9, s9, s53
	s_mov_b32 m0, s9
	s_nop 0
	global_load_lds_dwordx4 v166, s[10:11]
	s_add_u32 s10, s10, 0x2000
	s_addc_u32 s11, s11, 0
	s_add_i32 m0, s9, 0x2000
	s_nop 0
	global_load_lds_dwordx4 v166, s[10:11]
	s_add_i32 s9, s56, 2
	s_min_u32 s9, s9, s52
	s_lshl_b32 s58, s9, 14
	s_and_b32 s59, s57, 0xc000
	s_add_i32 s59, s59, s53
	s_add_i32 s9, s56, 3
	s_min_u32 s9, s9, s52
	s_lshl_b32 s10, s9, 14
	s_mov_b32 s11, 0
	s_add_u32 s10, s98, s10
	s_addc_u32 s11, s99, 0
	s_add_i32 s9, s57, 0x4000
	s_and_b32 s9, s9, 0xc000
	s_add_i32 s9, s9, s53
	s_waitcnt lgkmcnt(3)
	v_mfma_f32_32x32x16_bf16 v[226:241], v[128:131], v[146:149], v[98:113]
	ds_read_b128 v[128:131], v132 offset:512
	s_waitcnt lgkmcnt(3)
	v_mfma_f32_32x32x16_bf16 v[226:241], v[138:141], v[150:153], v[226:241]
	ds_read_b128 v[138:141], v132 offset:2560
	s_waitcnt lgkmcnt(3)
	v_mfma_f32_32x32x16_bf16 v[226:241], v[142:145], v[154:157], v[226:241]
	ds_read_b128 v[142:145], v132 offset:4608
	s_waitcnt lgkmcnt(3)
	v_mfma_f32_32x32x16_bf16 v[226:241], v[250:253], v[158:161], v[226:241]
	ds_read_b128 v[250:253], v132 offset:6656
	s_waitcnt lgkmcnt(3)
	v_mfma_f32_32x32x16_bf16 v[2:17], v[128:131], v[146:149], v[98:113]
	ds_read_b64_tr_b16 v[128:129], v133
	ds_read_b64_tr_b16 v[130:131], v133 offset:512
	s_waitcnt lgkmcnt(4)
	v_mfma_f32_32x32x16_bf16 v[2:17], v[138:141], v[150:153], v[2:17]
	ds_read_b64_tr_b16 v[138:139], v133 offset:4096
	ds_read_b64_tr_b16 v[140:141], v133 offset:4608
	s_waitcnt lgkmcnt(5)
	v_mfma_f32_32x32x16_bf16 v[2:17], v[142:145], v[154:157], v[2:17]
	ds_read_b64_tr_b16 v[142:143], v133 offset:8192
	ds_read_b64_tr_b16 v[144:145], v133 offset:8704
	s_waitcnt lgkmcnt(6)
	v_mfma_f32_32x32x16_bf16 v[2:17], v[250:253], v[158:161], v[2:17]
	ds_read_b64_tr_b16 v[250:251], v133 offset:12288
	ds_read_b64_tr_b16 v[252:253], v133 offset:12800
	s_branch .Latt_fast_pv
.Latt_fast_top:
	s_add_i32 s10, s57, 0xffff4000
	s_and_b32 s10, s10, 0xc000
	v_add_u32_e32 v133, s10, v185
	s_add_i32 s9, s56, 2
	s_min_u32 s9, s9, s52
	s_lshl_b32 s58, s9, 14
	s_and_b32 s59, s57, 0xc000
	s_add_i32 s59, s59, s53
	s_add_i32 s9, s56, 3
	s_min_u32 s9, s9, s52
	s_lshl_b32 s10, s9, 14
	s_mov_b32 s11, 0
	s_add_u32 s10, s98, s10
	s_addc_u32 s11, s99, 0
	s_add_i32 s9, s57, 0x4000
	s_and_b32 s9, s9, 0xc000
	s_add_i32 s9, s9, s53
	v_exp_f32_e32 v2, v2
	v_exp_f32_e32 v3, v3
	v_add_f32_e32 v243, v243, v2
	v_exp_f32_e32 v4, v4
	s_waitcnt lgkmcnt(3)
	v_mfma_f32_32x32x16_bf16 v[226:241], v[128:131], v[146:149], v[98:113]
	ds_read_b128 v[128:131], v132 offset:512
	v_add_f32_e32 v244, v244, v3
	v_exp_f32_e32 v5, v5
	v_add_f32_e32 v242, v242, v4
	v_cvt_pk_bf16_f32 v124, v2, v3
	v_add_f32_e32 v245, v245, v5
	v_exp_f32_e32 v6, v6
	v_exp_f32_e32 v7, v7
	v_add_f32_e32 v243, v243, v6
	v_cvt_pk_bf16_f32 v125, v4, v5
	s_waitcnt lgkmcnt(3)
	v_mfma_f32_32x32x16_bf16 v[226:241], v[138:141], v[150:153], v[226:241]
	ds_read_b128 v[138:141], v132 offset:2560
	v_add_f32_e32 v244, v244, v7
	v_exp_f32_e32 v8, v8
	v_exp_f32_e32 v9, v9
	v_add_f32_e32 v242, v242, v8
	v_cvt_pk_bf16_f32 v126, v6, v7
	v_add_f32_e32 v245, v245, v9
	v_cvt_pk_bf16_f32 v127, v8, v9
	v_exp_f32_e32 v10, v10
	v_exp_f32_e32 v11, v11
	s_waitcnt lgkmcnt(3)
	v_mfma_f32_32x32x16_bf16 v[226:241], v[142:145], v[154:157], v[226:241]
	ds_read_b128 v[142:145], v132 offset:4608
	v_add_f32_e32 v243, v243, v10
	v_exp_f32_e32 v12, v12
	v_add_f32_e32 v244, v244, v11
	v_exp_f32_e32 v13, v13
	v_add_f32_e32 v242, v242, v12
	v_cvt_pk_bf16_f32 v120, v10, v11
	v_add_f32_e32 v245, v245, v13
	v_exp_f32_e32 v14, v14
	v_exp_f32_e32 v15, v15
	s_waitcnt lgkmcnt(3)
	v_mfma_f32_32x32x16_bf16 v[226:241], v[250:253], v[158:161], v[226:241]
	ds_read_b128 v[250:253], v132 offset:6656
	v_add_f32_e32 v243, v243, v14
	v_cvt_pk_bf16_f32 v121, v12, v13
	v_add_f32_e32 v244, v244, v15
	v_exp_f32_e32 v16, v16
	v_exp_f32_e32 v17, v17
	v_add_f32_e32 v242, v242, v16
	v_cvt_pk_bf16_f32 v122, v14, v15
	v_add_f32_e32 v245, v245, v17
	v_cvt_pk_bf16_f32 v123, v16, v17
	s_waitcnt lgkmcnt(3)
	v_mfma_f32_32x32x16_bf16 v[2:17], v[128:131], v[146:149], v[98:113]
	ds_read_b64_tr_b16 v[128:129], v133
	ds_read_b64_tr_b16 v[130:131], v133 offset:512
	s_waitcnt lgkmcnt(4)
	v_mfma_f32_32x32x16_bf16 v[2:17], v[138:141], v[150:153], v[2:17]
	ds_read_b64_tr_b16 v[138:139], v133 offset:4096
	ds_read_b64_tr_b16 v[140:141], v133 offset:4608
	s_waitcnt lgkmcnt(5)
	v_mfma_f32_32x32x16_bf16 v[2:17], v[142:145], v[154:157], v[2:17]
	ds_read_b64_tr_b16 v[142:143], v133 offset:8192
	ds_read_b64_tr_b16 v[144:145], v133 offset:8704
	s_waitcnt lgkmcnt(6)
	v_mfma_f32_32x32x16_bf16 v[2:17], v[250:253], v[158:161], v[2:17]
	ds_read_b64_tr_b16 v[250:251], v133 offset:12288
	ds_read_b64_tr_b16 v[252:253], v133 offset:12800
; __device__ __forceinline__ int crow(int r, int hi) { return (r & 3) + 8 * (r >> 2) + 4 * hi; }
; __device__ __forceinline__ void att_qs(bf16x8 (&pn)[4], f32x16 (&o)[4], f32x16& osum, f32x16& negm, const bf16x8 (&qf)[4], float& m_hat, ...
;     ...
;     rm = xhalf_max(rm);
;     if (first_tile) {
;         m_hat += rm;
; #pragma unroll
;         for (int r = 0; r < 16; ++r) { c0[r] -= rm; c1[r] -= rm; negm[r] = -m_hat; }
;     } else if (__any(rm > 8.0f)) {
;         const float dl = fmaxf(rm, 0.f); m_hat += dl; const float f = __builtin_amdgcn_exp2f(-dl);
; #pragma unroll
;         for (int r = 0; r < 16; ++r) { c0[r] -= dl; c1[r] -= dl; negm[r] = -m_hat; }
;         if (hi == 0) scr[i32] = f;
;         asm volatile("s_waitcnt lgkmcnt(0)" ::: "memory");
; #pragma unroll
;         for (int r = 0; r < 16; ++r) { const float fr_ = scr[crow(r, hi)]; osum[r] *= fr_;
; #pragma unroll
;             for (int d = 0; d < 4; ++d) o[d][r] *= fr_; }
;     }
;     unsigned paw[16];
; #pragma unroll
;     for (int g = 0; g < 8; ++g) { const int b = (4 * g) & 15;
;         const float v0 = __builtin_amdgcn_exp2f(g < 4 ? c0[b] : c1[b]), v1 = __builtin_amdgcn_exp2f(g < 4 ? c0[b + 1] : c1[b + 1]);
;         const float v2 = __builtin_amdgcn_exp2f(g < 4 ? c0[b + 2] : c1[b + 2]), v3 = __builtin_amdgcn_exp2f(g < 4 ? c0[b + 3] : c1[b + 3]);
;         paw[2 * g] = pk2(v0, v1); paw[2 * g + 1] = pk2(v2, v3); }
; #pragma unroll
;     for (int k = 0; k < 4; ++k) { u32x4 w; w.x = paw[4 * k]; w.y = paw[4 * k + 1]; w.z = paw[4 * k + 2]; w.w = paw[4 * k + 3]; pn[k] = __builtin_bit_cast(bf16x8, w); }
; __device__ __forceinline__ void att_pv(const bf16x8 (&pp)[4], f32x16 (&o)[4], f32x16& osum, const LAS unsigned char* vb) {
;     ...
;     const bf16x8 ones = (bf16x8){0x3F80, 0x3F80, 0x3F80, 0x3F80, 0x3F80, 0x3F80, 0x3F80, 0x3F80};
;     ATT_VREADK(0);
; #pragma unroll
;     for (int ks = 0; ks < 4; ++ks) {
;         if (ks + 1 < 4) ATT_VREADK(ks + 1);
;         osum = __builtin_amdgcn_mfma_f32_32x32x16_bf16(pp[ks], ones, osum, 0, 0, 0);
; #pragma unroll
;         for (int d = 0; d < 4; ++d) { const int bk = ks & 1;
;             const bf16x8 vf = (bf16x8){vl[bk][d][0], vl[bk][d][1], vl[bk][d][2], vl[bk][d][3], vh[bk][d][0], vh[bk][d][1], vh[bk][d][2], vh[bk][d][3]};
;             o[d] = __builtin_amdgcn_mfma_f32_32x32x16_bf16(pp[ks], vf, o[d], 0, 0, 0); }
;     }
.Latt_fast_pv:
	s_waitcnt lgkmcnt(6)
	v_mfma_f32_32x32x16_bf16 v[34:49], v[134:137], v[128:131], v[34:49]
	ds_read_b64_tr_b16 v[128:129], v133 offset:1024
	ds_read_b64_tr_b16 v[130:131], v133 offset:1536
	s_mov_b32 m0, s9
	s_nop 0
	global_load_lds_dwordx4 v166, s[10:11]
	s_waitcnt lgkmcnt(6)
	v_mfma_f32_32x32x16_bf16 v[50:65], v[134:137], v[138:141], v[50:65]
	ds_read_b64_tr_b16 v[138:139], v133 offset:5120
	ds_read_b64_tr_b16 v[140:141], v133 offset:5632
	s_add_u32 s10, s10, 0x2000
	s_addc_u32 s11, s11, 0
	s_add_i32 m0, s9, 0x2000
	s_nop 0
	global_load_lds_dwordx4 v166, s[10:11]
	s_waitcnt lgkmcnt(6)
	v_mfma_f32_32x32x16_bf16 v[66:81], v[134:137], v[142:145], v[66:81]
	ds_read_b64_tr_b16 v[142:143], v133 offset:9216
	ds_read_b64_tr_b16 v[144:145], v133 offset:9728
	s_add_u32 s10, s100, s58
	s_addc_u32 s11, s101, 0
	s_add_i32 m0, s59, 0x10000
	s_nop 0
	global_load_lds_dwordx4 v166, s[10:11]
	s_waitcnt lgkmcnt(6)
	v_mfma_f32_32x32x16_bf16 v[82:97], v[134:137], v[250:253], v[82:97]
	ds_read_b64_tr_b16 v[250:251], v133 offset:13312
	ds_read_b64_tr_b16 v[252:253], v133 offset:13824
	s_add_u32 s10, s10, 0x2000
	s_addc_u32 s11, s11, 0
	s_add_i32 m0, s59, 0x12000
	s_nop 0
	global_load_lds_dwordx4 v166, s[10:11]
	s_waitcnt lgkmcnt(6)
	v_mfma_f32_32x32x16_bf16 v[34:49], v[114:117], v[128:131], v[34:49]
	ds_read_b64_tr_b16 v[128:129], v133 offset:2048
	ds_read_b64_tr_b16 v[130:131], v133 offset:2560
	v_max3_f32 v0, v226, v227, v228
	v_max3_f32 v225, v2, v3, v4
	v_max3_f32 v0, v0, v229, v230
	v_max3_f32 v225, v225, v5, v6
	s_waitcnt lgkmcnt(6)
	v_mfma_f32_32x32x16_bf16 v[50:65], v[114:117], v[138:141], v[50:65]
	ds_read_b64_tr_b16 v[138:139], v133 offset:6144
	ds_read_b64_tr_b16 v[140:141], v133 offset:6656
	v_max3_f32 v0, v0, v231, v232
	v_max3_f32 v225, v225, v7, v8
	v_max3_f32 v0, v0, v233, v234
	v_max3_f32 v225, v225, v9, v10
	s_waitcnt lgkmcnt(6)
	v_mfma_f32_32x32x16_bf16 v[66:81], v[114:117], v[142:145], v[66:81]
	ds_read_b64_tr_b16 v[142:143], v133 offset:10240
	ds_read_b64_tr_b16 v[144:145], v133 offset:10752
	v_max3_f32 v0, v0, v235, v236
	v_max3_f32 v225, v225, v11, v12
	v_max3_f32 v0, v0, v237, v238
	v_max3_f32 v225, v225, v13, v14
	s_waitcnt lgkmcnt(6)
	v_mfma_f32_32x32x16_bf16 v[82:97], v[114:117], v[250:253], v[82:97]
	ds_read_b64_tr_b16 v[250:251], v133 offset:14336
	ds_read_b64_tr_b16 v[252:253], v133 offset:14848
	v_max3_f32 v0, v0, v239, v240
	v_max3_f32 v225, v225, v15, v16
	v_max3_f32 v0, v0, v225, v241
	v_max3_f32 v0, v0, v17, v17
	v_cmp_lt_f32_e32 vcc, s36, v0
	s_cbranch_vccnz .Latt_fast_rescale
	s_waitcnt lgkmcnt(6)
	v_mfma_f32_32x32x16_bf16 v[34:49], v[124:127], v[128:131], v[34:49]
	ds_read_b64_tr_b16 v[128:129], v133 offset:3072
	ds_read_b64_tr_b16 v[130:131], v133 offset:3584
	v_exp_f32_e32 v226, v226
	v_exp_f32_e32 v227, v227
	v_add_f32_e32 v243, v243, v226
	v_exp_f32_e32 v228, v228
	v_add_f32_e32 v244, v244, v227
	s_waitcnt lgkmcnt(6)
	v_mfma_f32_32x32x16_bf16 v[50:65], v[124:127], v[138:141], v[50:65]
	ds_read_b64_tr_b16 v[138:139], v133 offset:7168
	ds_read_b64_tr_b16 v[140:141], v133 offset:7680
	v_exp_f32_e32 v229, v229
	v_add_f32_e32 v242, v242, v228
	v_cvt_pk_bf16_f32 v134, v226, v227
	v_add_f32_e32 v245, v245, v229
	v_exp_f32_e32 v230, v230
	s_waitcnt lgkmcnt(6)
	v_mfma_f32_32x32x16_bf16 v[66:81], v[124:127], v[142:145], v[66:81]
	ds_read_b64_tr_b16 v[142:143], v133 offset:11264
	ds_read_b64_tr_b16 v[144:145], v133 offset:11776
	v_exp_f32_e32 v231, v231
	v_add_f32_e32 v243, v243, v230
	v_cvt_pk_bf16_f32 v135, v228, v229
	v_add_f32_e32 v244, v244, v231
	v_exp_f32_e32 v232, v232
	s_waitcnt lgkmcnt(6)
	v_mfma_f32_32x32x16_bf16 v[82:97], v[124:127], v[250:253], v[82:97]
	ds_read_b64_tr_b16 v[250:251], v133 offset:15360
	ds_read_b64_tr_b16 v[252:253], v133 offset:15872
	v_exp_f32_e32 v233, v233
	v_add_f32_e32 v242, v242, v232
	v_cvt_pk_bf16_f32 v136, v230, v231
	v_add_f32_e32 v245, v245, v233
	v_cvt_pk_bf16_f32 v137, v232, v233
	s_waitcnt lgkmcnt(6)
	v_mfma_f32_32x32x16_bf16 v[34:49], v[120:123], v[128:131], v[34:49]
	s_add_i32 s9, s57, 0xffffc000
	s_and_b32 s9, s9, 0xc000
	v_add_u32_e32 v132, s9, v177
	ds_read_b128 v[128:131], v132
	v_exp_f32_e32 v234, v234
	v_exp_f32_e32 v235, v235
	v_add_f32_e32 v243, v243, v234
	v_exp_f32_e32 v236, v236
	v_add_f32_e32 v244, v244, v235
	s_waitcnt lgkmcnt(5)
	v_mfma_f32_32x32x16_bf16 v[50:65], v[120:123], v[138:141], v[50:65]
	ds_read_b128 v[138:141], v132 offset:2048
	v_exp_f32_e32 v237, v237
	v_add_f32_e32 v242, v242, v236
	v_cvt_pk_bf16_f32 v114, v234, v235
	v_add_f32_e32 v245, v245, v237
	v_exp_f32_e32 v238, v238
	s_waitcnt lgkmcnt(4)
	v_mfma_f32_32x32x16_bf16 v[66:81], v[120:123], v[142:145], v[66:81]
	ds_read_b128 v[142:145], v132 offset:4096
	v_exp_f32_e32 v239, v239
	v_add_f32_e32 v243, v243, v238
	v_cvt_pk_bf16_f32 v115, v236, v237
	v_add_f32_e32 v244, v244, v239
	v_exp_f32_e32 v240, v240
	s_waitcnt lgkmcnt(3)
	v_mfma_f32_32x32x16_bf16 v[82:97], v[120:123], v[250:253], v[82:97]
	ds_read_b128 v[250:253], v132 offset:6144
	v_exp_f32_e32 v241, v241
	v_add_f32_e32 v242, v242, v240
	v_cvt_pk_bf16_f32 v116, v238, v239
	v_add_f32_e32 v245, v245, v241
	v_cvt_pk_bf16_f32 v117, v240, v241

; #define LAS __attribute__((address_space(3)))
; __device__ __forceinline__ unsigned pk2(float lo, float hi) { f32x2_t v = {lo, hi}; bf16x2_t b = __builtin_convertvector(v, bf16x2_t); return __builtin_bit_cast(unsigned, b); }
; #define ATT_VREADK(ks) do { _Pragma("unroll") for (int d_ = 0; d_ < 4; ++d_) { vl[(ks) & 1][d_] = vtr(vb + d_ * 4096 + (ks) * 1024); vh[(ks) & 1][d_] = vtr(vb + d_ * 4096 + (ks) * 1024 + 512); } } while (0)
; __device__ __forceinline__ void att_qs(bf16x8 (&pn)[4], f32x16 (&o)[4], f32x16& osum, f32x16& negm, const bf16x8 (&qf)[4], float& m_hat, ...
;     ...
;     unsigned paw[16];
; #pragma unroll
;     for (int g = 0; g < 8; ++g) { const int b = (4 * g) & 15;
;         const float v0 = __builtin_amdgcn_exp2f(g < 4 ? c0[b] : c1[b]), v1 = __builtin_amdgcn_exp2f(g < 4 ? c0[b + 1] : c1[b + 1]);
;         const float v2 = __builtin_amdgcn_exp2f(g < 4 ? c0[b + 2] : c1[b + 2]), v3 = __builtin_amdgcn_exp2f(g < 4 ? c0[b + 3] : c1[b + 3]);
;         paw[2 * g] = pk2(v0, v1); paw[2 * g + 1] = pk2(v2, v3); }
; #pragma unroll
;     for (int k = 0; k < 4; ++k) { u32x4 w; w.x = paw[4 * k]; w.y = paw[4 * k + 1]; w.z = paw[4 * k + 2]; w.w = paw[4 * k + 3]; pn[k] = __builtin_bit_cast(bf16x8, w); }
;     __builtin_amdgcn_s_setprio(0);
; }
; __device__ __forceinline__ void att_pv(const bf16x8 (&pp)[4], f32x16 (&o)[4], f32x16& osum, const LAS unsigned char* vb) {
;     s16x4 vl[2][4], vh[2][4];
;     ...
;     const bf16x8 ones = (bf16x8){0x3F80, 0x3F80, 0x3F80, 0x3F80, 0x3F80, 0x3F80, 0x3F80, 0x3F80};
;     ATT_VREADK(0);
; #pragma unroll
;     for (int ks = 0; ks < 4; ++ks) {
;         if (ks + 1 < 4) ATT_VREADK(ks + 1);
;         osum = __builtin_amdgcn_mfma_f32_32x32x16_bf16(pp[ks], ones, osum, 0, 0, 0);
; #pragma unroll
;         for (int d = 0; d < 4; ++d) { const int bk = ks & 1;
;             const bf16x8 vf = (bf16x8){vl[bk][d][0], vl[bk][d][1], vl[bk][d][2], vl[bk][d][3], vh[bk][d][0], vh[bk][d][1], vh[bk][d][2], vh[bk][d][3]};
;             o[d] = __builtin_amdgcn_mfma_f32_32x32x16_bf16(pp[ks], vf, o[d], 0, 0, 0); }
;     }
.Latt_fast_exit:
	s_waitcnt vmcnt(4) lgkmcnt(0)
	s_barrier
	v_exp_f32_e32 v2, v2
	v_exp_f32_e32 v3, v3
	v_add_f32_e32 v243, v243, v2
	v_exp_f32_e32 v4, v4
	v_add_f32_e32 v244, v244, v3
	v_exp_f32_e32 v5, v5
	v_add_f32_e32 v242, v242, v4
	v_cvt_pk_bf16_f32 v124, v2, v3
	v_add_f32_e32 v245, v245, v5
	v_exp_f32_e32 v6, v6
	v_exp_f32_e32 v7, v7
	v_add_f32_e32 v243, v243, v6
	v_cvt_pk_bf16_f32 v125, v4, v5
	v_add_f32_e32 v244, v244, v7
	v_exp_f32_e32 v8, v8
	v_exp_f32_e32 v9, v9
	v_add_f32_e32 v242, v242, v8
	v_cvt_pk_bf16_f32 v126, v6, v7
	v_add_f32_e32 v245, v245, v9
	v_cvt_pk_bf16_f32 v127, v8, v9
	v_exp_f32_e32 v10, v10
	v_exp_f32_e32 v11, v11
	v_add_f32_e32 v243, v243, v10
	v_exp_f32_e32 v12, v12
	v_add_f32_e32 v244, v244, v11
	v_exp_f32_e32 v13, v13
	v_add_f32_e32 v242, v242, v12
	v_cvt_pk_bf16_f32 v120, v10, v11
	v_add_f32_e32 v245, v245, v13
	v_exp_f32_e32 v14, v14
	v_exp_f32_e32 v15, v15
	v_add_f32_e32 v243, v243, v14
	v_cvt_pk_bf16_f32 v121, v12, v13
	v_add_f32_e32 v244, v244, v15
	v_exp_f32_e32 v16, v16
	v_exp_f32_e32 v17, v17
	v_add_f32_e32 v242, v242, v16
	v_cvt_pk_bf16_f32 v122, v14, v15
	v_add_f32_e32 v245, v245, v17
	v_cvt_pk_bf16_f32 v123, v16, v17
	s_add_i32 s10, s57, 0xffff4000
	s_and_b32 s10, s10, 0xc000
	v_add_u32_e32 v133, s10, v185
	ds_read_b64_tr_b16 v[128:129], v133
	ds_read_b64_tr_b16 v[130:131], v133 offset:512
	ds_read_b64_tr_b16 v[138:139], v133 offset:4096
	ds_read_b64_tr_b16 v[140:141], v133 offset:4608
	ds_read_b64_tr_b16 v[142:143], v133 offset:8192
	ds_read_b64_tr_b16 v[144:145], v133 offset:8704
	ds_read_b64_tr_b16 v[250:251], v133 offset:12288
	ds_read_b64_tr_b16 v[252:253], v133 offset:12800
	s_waitcnt lgkmcnt(6)
	v_mfma_f32_32x32x16_bf16 v[34:49], v[134:137], v[128:131], v[34:49]
	ds_read_b64_tr_b16 v[128:129], v133 offset:1024
	ds_read_b64_tr_b16 v[130:131], v133 offset:1536
	s_waitcnt lgkmcnt(6)
	v_mfma_f32_32x32x16_bf16 v[50:65], v[134:137], v[138:141], v[50:65]
	ds_read_b64_tr_b16 v[138:139], v133 offset:5120
	ds_read_b64_tr_b16 v[140:141], v133 offset:5632
	s_waitcnt lgkmcnt(6)
	v_mfma_f32_32x32x16_bf16 v[66:81], v[134:137], v[142:145], v[66:81]
	ds_read_b64_tr_b16 v[142:143], v133 offset:9216
	ds_read_b64_tr_b16 v[144:145], v133 offset:9728
	s_waitcnt lgkmcnt(6)
	v_mfma_f32_32x32x16_bf16 v[82:97], v[134:137], v[250:253], v[82:97]
	ds_read_b64_tr_b16 v[250:251], v133 offset:13312
	ds_read_b64_tr_b16 v[252:253], v133 offset:13824
	s_waitcnt lgkmcnt(6)
	v_mfma_f32_32x32x16_bf16 v[34:49], v[114:117], v[128:131], v[34:49]
	ds_read_b64_tr_b16 v[128:129], v133 offset:2048
	ds_read_b64_tr_b16 v[130:131], v133 offset:2560
	s_waitcnt lgkmcnt(6)
	v_mfma_f32_32x32x16_bf16 v[50:65], v[114:117], v[138:141], v[50:65]
	ds_read_b64_tr_b16 v[138:139], v133 offset:6144
	ds_read_b64_tr_b16 v[140:141], v133 offset:6656
	s_waitcnt lgkmcnt(6)
	v_mfma_f32_32x32x16_bf16 v[66:81], v[114:117], v[142:145], v[66:81]
	ds_read_b64_tr_b16 v[142:143], v133 offset:10240
	ds_read_b64_tr_b16 v[144:145], v133 offset:10752
	s_waitcnt lgkmcnt(6)
	v_mfma_f32_32x32x16_bf16 v[82:97], v[114:117], v[250:253], v[82:97]
	ds_read_b64_tr_b16 v[250:251], v133 offset:14336
	ds_read_b64_tr_b16 v[252:253], v133 offset:14848
	s_waitcnt lgkmcnt(6)
	v_mfma_f32_32x32x16_bf16 v[34:49], v[124:127], v[128:131], v[34:49]
	ds_read_b64_tr_b16 v[128:129], v133 offset:3072
	ds_read_b64_tr_b16 v[130:131], v133 offset:3584
	s_waitcnt lgkmcnt(6)
	v_mfma_f32_32x32x16_bf16 v[50:65], v[124:127], v[138:141], v[50:65]
	ds_read_b64_tr_b16 v[138:139], v133 offset:7168
	ds_read_b64_tr_b16 v[140:141], v133 offset:7680
	s_waitcnt lgkmcnt(6)
	v_mfma_f32_32x32x16_bf16 v[66:81], v[124:127], v[142:145], v[66:81]
	ds_read_b64_tr_b16 v[142:143], v133 offset:11264
	ds_read_b64_tr_b16 v[144:145], v133 offset:11776
	s_waitcnt lgkmcnt(6)
	v_mfma_f32_32x32x16_bf16 v[82:97], v[124:127], v[250:253], v[82:97]
	ds_read_b64_tr_b16 v[250:251], v133 offset:15360
	ds_read_b64_tr_b16 v[252:253], v133 offset:15872
	s_waitcnt lgkmcnt(6)
	v_mfma_f32_32x32x16_bf16 v[34:49], v[120:123], v[128:131], v[34:49]
	s_waitcnt lgkmcnt(4)
	v_mfma_f32_32x32x16_bf16 v[50:65], v[120:123], v[138:141], v[50:65]
	s_waitcnt lgkmcnt(2)
	v_mfma_f32_32x32x16_bf16 v[66:81], v[120:123], v[142:145], v[66:81]
	s_waitcnt lgkmcnt(0)
	v_mfma_f32_32x32x16_bf16 v[82:97], v[120:123], v[250:253], v[82:97]
	v_add_f32_e32 v243, v243, v242
	v_add_f32_e32 v244, v244, v245
	v_add_f32_e32 v243, v243, v244
	v_mov_b32_e32 v244, v243
	s_nop 1
	v_permlane32_swap_b32_e32 v243, v244
	v_add_f32_e32 v243, v243, v244
	s_and_saveexec_b64 s[10:11], s[6:7]
	ds_write_b32 v224, v243
	s_or_b64 exec, exec, s[10:11]
	s_waitcnt lgkmcnt(0)
	v_add_u32_e32 v132, s51, v187
	ds_read_b128 v[128:131], v132
	ds_read_b128 v[138:141], v132 offset:32
	ds_read_b128 v[142:145], v132 offset:64
	ds_read_b128 v[250:253], v132 offset:96
	v_mov_b32_e32 v17, v248
	v_mov_b32_e32 v16, v118
	s_waitcnt lgkmcnt(0)
	v_add_f32_e32 v18, v18, v128
	v_add_f32_e32 v19, v19, v129
	v_add_f32_e32 v20, v20, v130
	v_add_f32_e32 v21, v21, v131
	v_add_f32_e32 v22, v22, v138
	v_add_f32_e32 v23, v23, v139
	v_add_f32_e32 v24, v24, v140
	v_add_f32_e32 v25, v25, v141
	v_add_f32_e32 v26, v26, v142
	v_add_f32_e32 v27, v27, v143
	v_add_f32_e32 v28, v28, v144
	v_add_f32_e32 v29, v29, v145
	v_add_f32_e32 v30, v30, v250
	v_add_f32_e32 v31, v31, v251
	v_add_f32_e32 v32, v32, v252
	v_add_f32_e32 v33, v33, v253
	s_cmp_eq_u32 s50, s56
	s_cbranch_scc1 .LBB0_695
	s_branch .LBB0_686
; __device__ __forceinline__ unsigned pk2(float lo, float hi) { f32x2_t v = {lo, hi}; bf16x2_t b = __builtin_convertvector(v, bf16x2_t); return __builtin_bit_cast(unsigned, b); }
; __device__ __forceinline__ int crow(int r, int hi) { return (r & 3) + 8 * (r >> 2) + 4 * hi; }
; __device__ __forceinline__ void att_qs(bf16x8 (&pn)[4], f32x16 (&o)[4], f32x16& osum, f32x16& negm, const bf16x8 (&qf)[4], float& m_hat, ...
;     ...
;     } else if (__any(rm > 8.0f)) {
;         const float dl = fmaxf(rm, 0.f); m_hat += dl; const float f = __builtin_amdgcn_exp2f(-dl);
; #pragma unroll
;         for (int r = 0; r < 16; ++r) { c0[r] -= dl; c1[r] -= dl; negm[r] = -m_hat; }
;         if (hi == 0) scr[i32] = f;
;         asm volatile("s_waitcnt lgkmcnt(0)" ::: "memory");
; #pragma unroll
;         for (int r = 0; r < 16; ++r) { const float fr_ = scr[crow(r, hi)]; osum[r] *= fr_;
; #pragma unroll
;             for (int d = 0; d < 4; ++d) o[d][r] *= fr_; }
;     }
;     unsigned paw[16];
; #pragma unroll
;     for (int g = 0; g < 8; ++g) { const int b = (4 * g) & 15;
;         const float v0 = __builtin_amdgcn_exp2f(g < 4 ? c0[b] : c1[b]), v1 = __builtin_amdgcn_exp2f(g < 4 ? c0[b + 1] : c1[b + 1]);
;         const float v2 = __builtin_amdgcn_exp2f(g < 4 ? c0[b + 2] : c1[b + 2]), v3 = __builtin_amdgcn_exp2f(g < 4 ? c0[b + 3] : c1[b + 3]);
;         paw[2 * g] = pk2(v0, v1); paw[2 * g + 1] = pk2(v2, v3); }
; #pragma unroll
;     for (int k = 0; k < 4; ++k) { u32x4 w; w.x = paw[4 * k]; w.y = paw[4 * k + 1]; w.z = paw[4 * k + 2]; w.w = paw[4 * k + 3]; pn[k] = __builtin_bit_cast(bf16x8, w); }
.Latt_fast_rescale:
	s_waitcnt lgkmcnt(0)
	v_mfma_f32_32x32x16_bf16 v[34:49], v[124:127], v[128:131], v[34:49]
	v_mfma_f32_32x32x16_bf16 v[50:65], v[124:127], v[138:141], v[50:65]
	v_mfma_f32_32x32x16_bf16 v[66:81], v[124:127], v[142:145], v[66:81]
	v_mfma_f32_32x32x16_bf16 v[82:97], v[124:127], v[250:253], v[82:97]
	ds_read_b64_tr_b16 v[128:129], v133 offset:3072
	ds_read_b64_tr_b16 v[130:131], v133 offset:3584
	ds_read_b64_tr_b16 v[138:139], v133 offset:7168
	ds_read_b64_tr_b16 v[140:141], v133 offset:7680
	ds_read_b64_tr_b16 v[142:143], v133 offset:11264
	ds_read_b64_tr_b16 v[144:145], v133 offset:11776
	ds_read_b64_tr_b16 v[250:251], v133 offset:15360
	ds_read_b64_tr_b16 v[252:253], v133 offset:15872
	s_waitcnt lgkmcnt(0)
	v_mfma_f32_32x32x16_bf16 v[34:49], v[120:123], v[128:131], v[34:49]
	v_mfma_f32_32x32x16_bf16 v[50:65], v[120:123], v[138:141], v[50:65]
	v_mfma_f32_32x32x16_bf16 v[66:81], v[120:123], v[142:145], v[66:81]
	v_mfma_f32_32x32x16_bf16 v[82:97], v[120:123], v[250:253], v[82:97]
	s_nop 15
	v_mov_b32_e32 v225, v0
	s_nop 1
	v_permlane32_swap_b32_e32 v0, v225
	v_max_f32_e32 v0, v0, v225
	v_max_f32_e32 v0, 0, v0
	v_add_f32_e32 v248, v248, v0
	v_exp_f32_e64 v225, -v0
	s_and_saveexec_b64 s[10:11], s[6:7]
	ds_write_b32 v224, v225
	s_or_b64 exec, exec, s[10:11]
	v_mul_f32_e32 v243, v243, v225
	v_mul_f32_e32 v244, v244, v225
	v_mul_f32_e32 v242, v242, v225
	v_mul_f32_e32 v245, v245, v225
	s_waitcnt lgkmcnt(0)
	v_add_u32_e32 v132, s51, v187
	ds_read_b128 v[128:131], v132
	ds_read_b128 v[138:141], v132 offset:32
	ds_read_b128 v[142:145], v132 offset:64
	ds_read_b128 v[250:253], v132 offset:96
	v_sub_f32_e32 v226, v226, v0
	v_sub_f32_e32 v227, v227, v0
	v_sub_f32_e32 v228, v228, v0
	v_sub_f32_e32 v229, v229, v0
	v_sub_f32_e32 v230, v230, v0
	v_sub_f32_e32 v231, v231, v0
	v_sub_f32_e32 v232, v232, v0
	v_sub_f32_e32 v233, v233, v0
	v_sub_f32_e32 v234, v234, v0
	v_sub_f32_e32 v235, v235, v0
	v_sub_f32_e32 v236, v236, v0
	v_sub_f32_e32 v237, v237, v0
	v_sub_f32_e32 v238, v238, v0
	v_sub_f32_e32 v239, v239, v0
	v_sub_f32_e32 v240, v240, v0
	v_sub_f32_e32 v241, v241, v0
	v_sub_f32_e32 v2, v2, v0
	v_sub_f32_e32 v3, v3, v0
	v_sub_f32_e32 v4, v4, v0
	v_sub_f32_e32 v5, v5, v0
	v_sub_f32_e32 v6, v6, v0
	v_sub_f32_e32 v7, v7, v0
	v_sub_f32_e32 v8, v8, v0
	v_sub_f32_e32 v9, v9, v0
	v_sub_f32_e32 v10, v10, v0
	v_sub_f32_e32 v11, v11, v0
	v_sub_f32_e32 v12, v12, v0
	v_sub_f32_e32 v13, v13, v0
	v_sub_f32_e32 v14, v14, v0
	v_sub_f32_e32 v15, v15, v0
	v_sub_f32_e32 v16, v16, v0
	v_sub_f32_e32 v17, v17, v0
	v_xor_b32_e32 v98, 0x80000000, v248
	v_mov_b32_e32 v99, v98
	v_mov_b32_e32 v100, v98
	v_mov_b32_e32 v101, v98
	v_mov_b32_e32 v102, v98
	v_mov_b32_e32 v103, v98
	v_mov_b32_e32 v104, v98
	v_mov_b32_e32 v105, v98
	v_mov_b32_e32 v106, v98
	v_mov_b32_e32 v107, v98
	v_mov_b32_e32 v108, v98
	v_mov_b32_e32 v109, v98
	v_mov_b32_e32 v110, v98
	v_mov_b32_e32 v111, v98
	v_mov_b32_e32 v112, v98
	v_mov_b32_e32 v113, v98
	s_waitcnt lgkmcnt(0)
	v_mul_f32_e32 v18, v18, v128
	v_mul_f32_e32 v34, v34, v128
	v_mul_f32_e32 v50, v50, v128
	v_mul_f32_e32 v66, v66, v128
	v_mul_f32_e32 v82, v82, v128
	v_mul_f32_e32 v19, v19, v129
	v_mul_f32_e32 v35, v35, v129
	v_mul_f32_e32 v51, v51, v129
	v_mul_f32_e32 v67, v67, v129
	v_mul_f32_e32 v83, v83, v129
	v_mul_f32_e32 v20, v20, v130
	v_mul_f32_e32 v36, v36, v130
	v_mul_f32_e32 v52, v52, v130
	v_mul_f32_e32 v68, v68, v130
	v_mul_f32_e32 v84, v84, v130
	v_mul_f32_e32 v21, v21, v131
	v_mul_f32_e32 v37, v37, v131
	v_mul_f32_e32 v53, v53, v131
	v_mul_f32_e32 v69, v69, v131
	v_mul_f32_e32 v85, v85, v131
	v_mul_f32_e32 v22, v22, v138
	v_mul_f32_e32 v38, v38, v138
	v_mul_f32_e32 v54, v54, v138
	v_mul_f32_e32 v70, v70, v138
	v_mul_f32_e32 v86, v86, v138
	v_mul_f32_e32 v23, v23, v139
	v_mul_f32_e32 v39, v39, v139
	v_mul_f32_e32 v55, v55, v139
	v_mul_f32_e32 v71, v71, v139
	v_mul_f32_e32 v87, v87, v139
	v_mul_f32_e32 v24, v24, v140
	v_mul_f32_e32 v40, v40, v140
	v_mul_f32_e32 v56, v56, v140
	v_mul_f32_e32 v72, v72, v140
	v_mul_f32_e32 v88, v88, v140
	v_mul_f32_e32 v25, v25, v141
	v_mul_f32_e32 v41, v41, v141
	v_mul_f32_e32 v57, v57, v141
	v_mul_f32_e32 v73, v73, v141
	v_mul_f32_e32 v89, v89, v141
	v_mul_f32_e32 v26, v26, v142
	v_mul_f32_e32 v42, v42, v142
	v_mul_f32_e32 v58, v58, v142
	v_mul_f32_e32 v74, v74, v142
	v_mul_f32_e32 v90, v90, v142
	v_mul_f32_e32 v27, v27, v143
	v_mul_f32_e32 v43, v43, v143
	v_mul_f32_e32 v59, v59, v143
	v_mul_f32_e32 v75, v75, v143
	v_mul_f32_e32 v91, v91, v143
	v_mul_f32_e32 v28, v28, v144
	v_mul_f32_e32 v44, v44, v144
	v_mul_f32_e32 v60, v60, v144
	v_mul_f32_e32 v76, v76, v144
	v_mul_f32_e32 v92, v92, v144
	v_mul_f32_e32 v29, v29, v145
	v_mul_f32_e32 v45, v45, v145
	v_mul_f32_e32 v61, v61, v145
	v_mul_f32_e32 v77, v77, v145
	v_mul_f32_e32 v93, v93, v145
	v_mul_f32_e32 v30, v30, v250
	v_mul_f32_e32 v46, v46, v250
	v_mul_f32_e32 v62, v62, v250
	v_mul_f32_e32 v78, v78, v250
	v_mul_f32_e32 v94, v94, v250
	v_mul_f32_e32 v31, v31, v251
	v_mul_f32_e32 v47, v47, v251
	v_mul_f32_e32 v63, v63, v251
	v_mul_f32_e32 v79, v79, v251
	v_mul_f32_e32 v95, v95, v251
	v_mul_f32_e32 v32, v32, v252
	v_mul_f32_e32 v48, v48, v252
	v_mul_f32_e32 v64, v64, v252
	v_mul_f32_e32 v80, v80, v252
	v_mul_f32_e32 v96, v96, v252
	v_mul_f32_e32 v33, v33, v253
	v_mul_f32_e32 v49, v49, v253
	v_mul_f32_e32 v65, v65, v253
	v_mul_f32_e32 v81, v81, v253
	v_mul_f32_e32 v97, v97, v253
	v_exp_f32_e32 v226, v226
	v_exp_f32_e32 v227, v227
	v_add_f32_e32 v243, v243, v226
	v_exp_f32_e32 v228, v228
	v_add_f32_e32 v244, v244, v227
	v_exp_f32_e32 v229, v229
	v_add_f32_e32 v242, v242, v228
	v_cvt_pk_bf16_f32 v134, v226, v227
	v_add_f32_e32 v245, v245, v229
	v_exp_f32_e32 v230, v230
	v_exp_f32_e32 v231, v231
	v_add_f32_e32 v243, v243, v230
	v_cvt_pk_bf16_f32 v135, v228, v229
	v_add_f32_e32 v244, v244, v231
	v_exp_f32_e32 v232, v232
	v_exp_f32_e32 v233, v233
	v_add_f32_e32 v242, v242, v232
	v_cvt_pk_bf16_f32 v136, v230, v231
	v_add_f32_e32 v245, v245, v233
	v_cvt_pk_bf16_f32 v137, v232, v233
	v_exp_f32_e32 v234, v234
	v_exp_f32_e32 v235, v235
	v_add_f32_e32 v243, v243, v234
	v_exp_f32_e32 v236, v236
	v_add_f32_e32 v244, v244, v235
	v_exp_f32_e32 v237, v237
	v_add_f32_e32 v242, v242, v236
	v_cvt_pk_bf16_f32 v114, v234, v235
	v_add_f32_e32 v245, v245, v237
	v_exp_f32_e32 v238, v238
	v_exp_f32_e32 v239, v239
	v_add_f32_e32 v243, v243, v238
	v_cvt_pk_bf16_f32 v115, v236, v237
	v_add_f32_e32 v244, v244, v239
	v_exp_f32_e32 v240, v240
	v_exp_f32_e32 v241, v241
	v_add_f32_e32 v242, v242, v240
	v_cvt_pk_bf16_f32 v116, v238, v239
	v_add_f32_e32 v245, v245, v241
	v_cvt_pk_bf16_f32 v117, v240, v241
	s_waitcnt lgkmcnt(0)
	s_add_i32 s9, s57, 0xffffc000
	s_and_b32 s9, s9, 0xc000
	v_add_u32_e32 v132, s9, v177
	ds_read_b128 v[128:131], v132
	ds_read_b128 v[138:141], v132 offset:2048
	ds_read_b128 v[142:145], v132 offset:4096
	ds_read_b128 v[250:253], v132 offset:6144
	s_branch .Latt_fast_end
